# skinny (sample-row) FFN-down GEMM K loops double-buffered: 24 loads in flight per wave instead of 2-3 serialized round trips per 128-deep step
# baseline (speedup 1.0000x reference)
; template <bool PAIR, class F>
; __device__ __forceinline__ void skinny(const bf16_t* A, int lda, const bf16_t* Bt, int ldb, int K, int tile_lo, int tile_hi, int kmode, int bx, int G, int tid_, LAS unsigned char* lds, F f) {
;     ...
;         const int rbp = un & 3, cgrp = un >> 2, tile = tile_lo + cgrp / GPT, cgp = (cgrp % GPT) * 4 + cgl;
;         const int n0 = tile * 256 + cgp * 16, row0 = MP + rbp * 32 + fr;
;         const bf16_t* ap = A + (size_t)row0 * lda + (kmode ? 256 * (tile >> 1) : 0) + fq * 8;
;         const bf16_t* bp = Bt + (size_t)(n0 + fr) * ldb + fq * 8;
;         f32x4 a00 = (f32x4){0.f, 0.f, 0.f, 0.f}, a01 = a00, a10 = a00, a11 = a00;
;         for (int k0 = kbeg; k0 < kbeg + Kh; k0 += 128) {
; #pragma unroll
;             for (int kk = 0; kk < 128; kk += 32) {
;                 const bf16x8 x0 = *(const bf16x8*)(ap + k0 + kk), x1 = *(const bf16x8*)(ap + (size_t)16 * lda + k0 + kk), b = *(const bf16x8*)(bp + k0 + kk);
;                 a00 = __builtin_amdgcn_mfma_f32_16x16x32_bf16(b, x0, a00, 0, 0, 0); a01 = __builtin_amdgcn_mfma_f32_16x16x32_bf16(b, x1, a01, 0, 0, 0);
;                 if (PAIR) { const bf16x8 b2 = *(const bf16x8*)(bp + (size_t)128 * ldb + k0 + kk);
;                     a10 = __builtin_amdgcn_mfma_f32_16x16x32_bf16(b2, x0, a10, 0, 0, 0); a11 = __builtin_amdgcn_mfma_f32_16x16x32_bf16(b2, x1, a11, 0, 0, 0); }
;             }
;         }
;         if (kh == 1) { X[0] = a00; X[1] = a01; if (PAIR) { X[2] = a10; X[3] = a11; } }
.LBB0_427:
	s_ashr_i32 s20, s24, 2
	s_lshr_b32 s21, s20, 30
	s_add_i32 s25, s20, s21
	s_and_b32 s21, s25, 0x3fffffc
	s_sub_i32 s20, s20, s21
	s_lshl_b32 s20, s20, 6
	s_or_b32 s21, s20, s13
	s_lshl_b32 s20, s24, 5
	s_and_b32 s20, s20, 0x60
	v_or_b32_e32 v22, s20, v18
	s_lshl_b32 s20, s25, 6
	s_and_b32 s20, s20, 0xffffff00
	v_or_b32_e32 v23, 0x4000, v22
	s_add_i32 s25, s21, s20
	v_mul_u32_u24_e32 v0, 0xb00, v23
	v_or_b32_e32 v1, s25, v18
	v_lshlrev_b32_e32 v8, 1, v0
	v_mad_i64_i32 v[14:15], s[26:27], v1, s23, v[12:13]
	v_mov_b64_e32 v[16:17], v[10:11]
	s_mov_b32 s25, s22
	v_mov_b32_e32 v4, v9
	v_mov_b32_e32 v5, v9
	v_mov_b32_e32 v6, v9
	v_mov_b32_e32 v7, v9
	v_mov_b32_e32 v0, v9
	v_mov_b32_e32 v1, v9
	v_mov_b32_e32 v2, v9
	v_mov_b32_e32 v3, v9
	s_movk_i32 s25, 10
	v_lshl_add_u64 v[126:127], v[16:17], 0, v[8:9]
	v_lshl_add_u64 v[124:125], v[16:17], 0, v[14:15]
	v_add_co_u32_e32 v52, vcc, 0x9e00000, v126
	s_nop 1
	v_addc_co_u32_e32 v53, vcc, 0, v127, vcc
	v_add_co_u32_e32 v54, vcc, 0x9e16000, v126
	s_nop 1
	v_addc_co_u32_e32 v55, vcc, 0, v127, vcc
	v_lshl_add_u64 v[16:17], v[16:17], 0, s[8:9]
	global_load_dwordx4 v[24:27], v[124:125], off offset:-128
	global_load_dwordx4 v[28:31], v[124:125], off offset:-64
	global_load_dwordx4 v[32:35], v[124:125], off
	global_load_dwordx4 v[36:39], v[124:125], off offset:64
	global_load_dwordx4 v[40:43], v[52:53], off
	global_load_dwordx4 v[48:51], v[54:55], off
	global_load_dwordx4 v[44:47], v[52:53], off offset:64
	global_load_dwordx4 v[64:67], v[54:55], off offset:64
	global_load_dwordx4 v[56:59], v[52:53], off offset:128
	global_load_dwordx4 v[68:71], v[54:55], off offset:128
	global_load_dwordx4 v[60:63], v[52:53], off offset:192
	global_load_dwordx4 v[72:75], v[54:55], off offset:192
.Lsk2_loop:
	s_cmp_eq_u32 s25, 0
	s_cbranch_scc1 .Lsk2_lastA
	v_lshl_add_u64 v[126:127], v[16:17], 0, v[8:9]
	v_lshl_add_u64 v[124:125], v[16:17], 0, v[14:15]
	v_add_co_u32_e32 v52, vcc, 0x9e00000, v126
	s_nop 1
	v_addc_co_u32_e32 v53, vcc, 0, v127, vcc
	v_add_co_u32_e32 v54, vcc, 0x9e16000, v126
	s_nop 1
	v_addc_co_u32_e32 v55, vcc, 0, v127, vcc
	v_lshl_add_u64 v[16:17], v[16:17], 0, s[8:9]
	global_load_dwordx4 v[76:79], v[124:125], off offset:-128
	global_load_dwordx4 v[80:83], v[124:125], off offset:-64
	global_load_dwordx4 v[84:87], v[124:125], off
	global_load_dwordx4 v[88:91], v[124:125], off offset:64
	global_load_dwordx4 v[92:95], v[52:53], off
	global_load_dwordx4 v[108:111], v[54:55], off
	global_load_dwordx4 v[96:99], v[52:53], off offset:64
	global_load_dwordx4 v[112:115], v[54:55], off offset:64
	global_load_dwordx4 v[100:103], v[52:53], off offset:128
	global_load_dwordx4 v[116:119], v[54:55], off offset:128
	global_load_dwordx4 v[104:107], v[52:53], off offset:192
	global_load_dwordx4 v[120:123], v[54:55], off offset:192
	s_sub_u32 s25, s25, 1
	s_waitcnt vmcnt(12)
	v_mfma_f32_16x16x32_bf16 v[4:7], v[24:27], v[40:43], v[4:7]
	v_mfma_f32_16x16x32_bf16 v[0:3], v[24:27], v[48:51], v[0:3]
	v_mfma_f32_16x16x32_bf16 v[4:7], v[28:31], v[44:47], v[4:7]
	v_mfma_f32_16x16x32_bf16 v[0:3], v[28:31], v[64:67], v[0:3]
	v_mfma_f32_16x16x32_bf16 v[4:7], v[32:35], v[56:59], v[4:7]
	v_mfma_f32_16x16x32_bf16 v[0:3], v[32:35], v[68:71], v[0:3]
	v_mfma_f32_16x16x32_bf16 v[4:7], v[36:39], v[60:63], v[4:7]
	v_mfma_f32_16x16x32_bf16 v[0:3], v[36:39], v[72:75], v[0:3]
	s_cmp_eq_u32 s25, 0
	s_cbranch_scc1 .Lsk2_lastB
	v_lshl_add_u64 v[126:127], v[16:17], 0, v[8:9]
	v_lshl_add_u64 v[124:125], v[16:17], 0, v[14:15]
	v_add_co_u32_e32 v52, vcc, 0x9e00000, v126
	s_nop 1
	v_addc_co_u32_e32 v53, vcc, 0, v127, vcc
	v_add_co_u32_e32 v54, vcc, 0x9e16000, v126
	s_nop 1
	v_addc_co_u32_e32 v55, vcc, 0, v127, vcc
	v_lshl_add_u64 v[16:17], v[16:17], 0, s[8:9]
	global_load_dwordx4 v[24:27], v[124:125], off offset:-128
	global_load_dwordx4 v[28:31], v[124:125], off offset:-64
	global_load_dwordx4 v[32:35], v[124:125], off
	global_load_dwordx4 v[36:39], v[124:125], off offset:64
	global_load_dwordx4 v[40:43], v[52:53], off
	global_load_dwordx4 v[48:51], v[54:55], off
	global_load_dwordx4 v[44:47], v[52:53], off offset:64
	global_load_dwordx4 v[64:67], v[54:55], off offset:64
	global_load_dwordx4 v[56:59], v[52:53], off offset:128
	global_load_dwordx4 v[68:71], v[54:55], off offset:128
	global_load_dwordx4 v[60:63], v[52:53], off offset:192
	global_load_dwordx4 v[72:75], v[54:55], off offset:192
	s_sub_u32 s25, s25, 1
	s_waitcnt vmcnt(12)
	v_mfma_f32_16x16x32_bf16 v[4:7], v[76:79], v[92:95], v[4:7]
	v_mfma_f32_16x16x32_bf16 v[0:3], v[76:79], v[108:111], v[0:3]
	v_mfma_f32_16x16x32_bf16 v[4:7], v[80:83], v[96:99], v[4:7]
	v_mfma_f32_16x16x32_bf16 v[0:3], v[80:83], v[112:115], v[0:3]
	v_mfma_f32_16x16x32_bf16 v[4:7], v[84:87], v[100:103], v[4:7]
	v_mfma_f32_16x16x32_bf16 v[0:3], v[84:87], v[116:119], v[0:3]
	v_mfma_f32_16x16x32_bf16 v[4:7], v[88:91], v[104:107], v[4:7]
	v_mfma_f32_16x16x32_bf16 v[0:3], v[88:91], v[120:123], v[0:3]
	s_branch .Lsk2_loop
.Lsk2_lastA:
	s_waitcnt vmcnt(0)
	v_mfma_f32_16x16x32_bf16 v[4:7], v[24:27], v[40:43], v[4:7]
	v_mfma_f32_16x16x32_bf16 v[0:3], v[24:27], v[48:51], v[0:3]
	v_mfma_f32_16x16x32_bf16 v[4:7], v[28:31], v[44:47], v[4:7]
	v_mfma_f32_16x16x32_bf16 v[0:3], v[28:31], v[64:67], v[0:3]
	v_mfma_f32_16x16x32_bf16 v[4:7], v[32:35], v[56:59], v[4:7]
	v_mfma_f32_16x16x32_bf16 v[0:3], v[32:35], v[68:71], v[0:3]
	v_mfma_f32_16x16x32_bf16 v[4:7], v[36:39], v[60:63], v[4:7]
	v_mfma_f32_16x16x32_bf16 v[0:3], v[36:39], v[72:75], v[0:3]
	s_branch .Lsk2_done
.Lsk2_lastB:
	s_waitcnt vmcnt(0)
	v_mfma_f32_16x16x32_bf16 v[4:7], v[76:79], v[92:95], v[4:7]
	v_mfma_f32_16x16x32_bf16 v[0:3], v[76:79], v[108:111], v[0:3]
	v_mfma_f32_16x16x32_bf16 v[4:7], v[80:83], v[96:99], v[4:7]
	v_mfma_f32_16x16x32_bf16 v[0:3], v[80:83], v[112:115], v[0:3]
	v_mfma_f32_16x16x32_bf16 v[4:7], v[84:87], v[100:103], v[4:7]
	v_mfma_f32_16x16x32_bf16 v[0:3], v[84:87], v[116:119], v[0:3]
	v_mfma_f32_16x16x32_bf16 v[4:7], v[88:91], v[104:107], v[4:7]
	v_mfma_f32_16x16x32_bf16 v[0:3], v[88:91], v[120:123], v[0:3]
.Lsk2_done:
	s_nop 7
	s_andn2_b64 vcc, exec, s[2:3]
	s_cbranch_vccnz .LBB0_431
	s_nop 2
	ds_write_b128 v20, v[4:7] offset:32768
	s_nop 0
	ds_write_b128 v20, v[0:3] offset:32784

; template <bool PAIR, class F>
; __device__ __forceinline__ void skinny(const bf16_t* A, int lda, const bf16_t* Bt, int ldb, int K, int tile_lo, int tile_hi, int kmode, int bx, int G, int tid_, LAS unsigned char* lds, F f) {
;     ...
;         const int rbp = un & 3, cgrp = un >> 2, tile = tile_lo + cgrp / GPT, cgp = (cgrp % GPT) * 4 + cgl;
;         const int n0 = tile * 256 + cgp * 16, row0 = MP + rbp * 32 + fr;
;         const bf16_t* ap = A + (size_t)row0 * lda + (kmode ? 256 * (tile >> 1) : 0) + fq * 8;
;         const bf16_t* bp = Bt + (size_t)(n0 + fr) * ldb + fq * 8;
;         f32x4 a00 = (f32x4){0.f, 0.f, 0.f, 0.f}, a01 = a00, a10 = a00, a11 = a00;
;         for (int k0 = kbeg; k0 < kbeg + Kh; k0 += 128) {
; #pragma unroll
;             for (int kk = 0; kk < 128; kk += 32) {
;                 const bf16x8 x0 = *(const bf16x8*)(ap + k0 + kk), x1 = *(const bf16x8*)(ap + (size_t)16 * lda + k0 + kk), b = *(const bf16x8*)(bp + k0 + kk);
;                 a00 = __builtin_amdgcn_mfma_f32_16x16x32_bf16(b, x0, a00, 0, 0, 0); a01 = __builtin_amdgcn_mfma_f32_16x16x32_bf16(b, x1, a01, 0, 0, 0);
;                 if (PAIR) { const bf16x8 b2 = *(const bf16x8*)(bp + (size_t)128 * ldb + k0 + kk);
;                     a10 = __builtin_amdgcn_mfma_f32_16x16x32_bf16(b2, x0, a10, 0, 0, 0); a11 = __builtin_amdgcn_mfma_f32_16x16x32_bf16(b2, x1, a11, 0, 0, 0); }
;             }
;         }
.LBB0_1935:
	s_ashr_i32 s18, s23, 2
	s_lshr_b32 s19, s18, 30
	s_add_i32 s24, s18, s19
	s_and_b32 s19, s24, 0x3fffffc
	s_sub_i32 s18, s18, s19
	s_lshl_b32 s18, s18, 6
	s_or_b32 s19, s18, s17
	s_lshl_b32 s18, s23, 5
	s_and_b32 s18, s18, 0x60
	v_or_b32_e32 v22, s18, v18
	s_lshl_b32 s18, s24, 6
	s_and_b32 s18, s18, 0xffffff00
	s_add_i32 s24, s19, s18
	v_or_b32_e32 v23, 0x4000, v22
	v_or_b32_e32 v1, s24, v18
	v_mul_u32_u24_e32 v0, 0xb00, v23
	v_mad_i64_i32 v[14:15], s[24:25], v1, s22, v[12:13]
	v_lshlrev_b32_e32 v8, 1, v0
	v_mov_b64_e32 v[16:17], v[10:11]
	s_mov_b32 s24, s21
	v_mov_b32_e32 v4, v9
	v_mov_b32_e32 v5, v9
	v_mov_b32_e32 v6, v9
	v_mov_b32_e32 v7, v9
	v_mov_b32_e32 v0, v9
	v_mov_b32_e32 v1, v9
	v_mov_b32_e32 v2, v9
	v_mov_b32_e32 v3, v9
	s_movk_i32 s24, 10
	v_lshl_add_u64 v[126:127], v[16:17], 0, v[8:9]
	v_lshl_add_u64 v[124:125], v[16:17], 0, v[14:15]
	v_add_co_u32_e32 v52, vcc, 0x9e00000, v126
	s_nop 1
	v_addc_co_u32_e32 v53, vcc, 0, v127, vcc
	v_add_co_u32_e32 v54, vcc, 0x9e16000, v126
	s_nop 1
	v_addc_co_u32_e32 v55, vcc, 0, v127, vcc
	v_lshl_add_u64 v[16:17], v[16:17], 0, s[12:13]
	global_load_dwordx4 v[24:27], v[124:125], off offset:-128
	global_load_dwordx4 v[28:31], v[124:125], off offset:-64
	global_load_dwordx4 v[32:35], v[124:125], off
	global_load_dwordx4 v[36:39], v[124:125], off offset:64
	global_load_dwordx4 v[40:43], v[52:53], off
	global_load_dwordx4 v[48:51], v[54:55], off
	global_load_dwordx4 v[44:47], v[52:53], off offset:64
	global_load_dwordx4 v[64:67], v[54:55], off offset:64
	global_load_dwordx4 v[56:59], v[52:53], off offset:128
	global_load_dwordx4 v[68:71], v[54:55], off offset:128
	global_load_dwordx4 v[60:63], v[52:53], off offset:192
	global_load_dwordx4 v[72:75], v[54:55], off offset:192
.Lsk17_loop:
	s_cmp_eq_u32 s24, 0
	s_cbranch_scc1 .Lsk17_lastA
	v_lshl_add_u64 v[126:127], v[16:17], 0, v[8:9]
	v_lshl_add_u64 v[124:125], v[16:17], 0, v[14:15]
	v_add_co_u32_e32 v52, vcc, 0x9e00000, v126
	s_nop 1
	v_addc_co_u32_e32 v53, vcc, 0, v127, vcc
	v_add_co_u32_e32 v54, vcc, 0x9e16000, v126
	s_nop 1
	v_addc_co_u32_e32 v55, vcc, 0, v127, vcc
	v_lshl_add_u64 v[16:17], v[16:17], 0, s[12:13]
	global_load_dwordx4 v[76:79], v[124:125], off offset:-128
	global_load_dwordx4 v[80:83], v[124:125], off offset:-64
	global_load_dwordx4 v[84:87], v[124:125], off
	global_load_dwordx4 v[88:91], v[124:125], off offset:64
	global_load_dwordx4 v[92:95], v[52:53], off
	global_load_dwordx4 v[108:111], v[54:55], off
	global_load_dwordx4 v[96:99], v[52:53], off offset:64
	global_load_dwordx4 v[112:115], v[54:55], off offset:64
	global_load_dwordx4 v[100:103], v[52:53], off offset:128
	global_load_dwordx4 v[116:119], v[54:55], off offset:128
	global_load_dwordx4 v[104:107], v[52:53], off offset:192
	global_load_dwordx4 v[120:123], v[54:55], off offset:192
	s_sub_u32 s24, s24, 1
	s_waitcnt vmcnt(12)
	v_mfma_f32_16x16x32_bf16 v[4:7], v[24:27], v[40:43], v[4:7]
	v_mfma_f32_16x16x32_bf16 v[0:3], v[24:27], v[48:51], v[0:3]
	v_mfma_f32_16x16x32_bf16 v[4:7], v[28:31], v[44:47], v[4:7]
	v_mfma_f32_16x16x32_bf16 v[0:3], v[28:31], v[64:67], v[0:3]
	v_mfma_f32_16x16x32_bf16 v[4:7], v[32:35], v[56:59], v[4:7]
	v_mfma_f32_16x16x32_bf16 v[0:3], v[32:35], v[68:71], v[0:3]
	v_mfma_f32_16x16x32_bf16 v[4:7], v[36:39], v[60:63], v[4:7]
	v_mfma_f32_16x16x32_bf16 v[0:3], v[36:39], v[72:75], v[0:3]
	s_cmp_eq_u32 s24, 0
	s_cbranch_scc1 .Lsk17_lastB
	v_lshl_add_u64 v[126:127], v[16:17], 0, v[8:9]
	v_lshl_add_u64 v[124:125], v[16:17], 0, v[14:15]
	v_add_co_u32_e32 v52, vcc, 0x9e00000, v126
	s_nop 1
	v_addc_co_u32_e32 v53, vcc, 0, v127, vcc
	v_add_co_u32_e32 v54, vcc, 0x9e16000, v126
	s_nop 1
	v_addc_co_u32_e32 v55, vcc, 0, v127, vcc
	v_lshl_add_u64 v[16:17], v[16:17], 0, s[12:13]
	global_load_dwordx4 v[24:27], v[124:125], off offset:-128
	global_load_dwordx4 v[28:31], v[124:125], off offset:-64
	global_load_dwordx4 v[32:35], v[124:125], off
	global_load_dwordx4 v[36:39], v[124:125], off offset:64
	global_load_dwordx4 v[40:43], v[52:53], off
	global_load_dwordx4 v[48:51], v[54:55], off
	global_load_dwordx4 v[44:47], v[52:53], off offset:64
	global_load_dwordx4 v[64:67], v[54:55], off offset:64
	global_load_dwordx4 v[56:59], v[52:53], off offset:128
	global_load_dwordx4 v[68:71], v[54:55], off offset:128
	global_load_dwordx4 v[60:63], v[52:53], off offset:192
	global_load_dwordx4 v[72:75], v[54:55], off offset:192
	s_sub_u32 s24, s24, 1
	s_waitcnt vmcnt(12)
	v_mfma_f32_16x16x32_bf16 v[4:7], v[76:79], v[92:95], v[4:7]
	v_mfma_f32_16x16x32_bf16 v[0:3], v[76:79], v[108:111], v[0:3]
	v_mfma_f32_16x16x32_bf16 v[4:7], v[80:83], v[96:99], v[4:7]
	v_mfma_f32_16x16x32_bf16 v[0:3], v[80:83], v[112:115], v[0:3]
	v_mfma_f32_16x16x32_bf16 v[4:7], v[84:87], v[100:103], v[4:7]
	v_mfma_f32_16x16x32_bf16 v[0:3], v[84:87], v[116:119], v[0:3]
	v_mfma_f32_16x16x32_bf16 v[4:7], v[88:91], v[104:107], v[4:7]
	v_mfma_f32_16x16x32_bf16 v[0:3], v[88:91], v[120:123], v[0:3]
	s_branch .Lsk17_loop

; template <bool PAIR, class F>
; __device__ __forceinline__ void skinny(const bf16_t* A, int lda, const bf16_t* Bt, int ldb, int K, int tile_lo, int tile_hi, int kmode, int bx, int G, int tid_, LAS unsigned char* lds, F f) {
;     ...
;         }
;         if (kh == 1) { X[0] = a00; X[1] = a01; if (PAIR) { X[2] = a10; X[3] = a11; } }
;         __syncthreads();
.Lsk17_done:
	s_nop 7
	s_andn2_b64 vcc, exec, s[2:3]
	s_cbranch_vccnz .LBB0_1939
	s_nop 3
	ds_write_b128 v20, v[4:7] offset:32768
	ds_write_b128 v20, v[0:3] offset:32784
